# P8 accumulator zeroing moved from the tile prologue into the first K iteration behind the issued LDS reads (blocks 1 and 2)
# speedup vs baseline: 1.0117x; 1.0004x over previous
.LBB0_876:
	s_ashr_i32 s27, s26, 31
	s_lshl_b64 s[28:29], s[26:27], 19
	s_add_u32 s28, s66, s28
	s_addc_u32 s29, s67, s29
	s_and_b64 s[30:31], s[4:5], exec
	s_cselect_b32 s27, s29, s37
	s_cselect_b32 s57, s28, s36
	s_ashr_i32 s25, s24, 31
	s_lshl_b64 s[30:31], s[24:25], 19
	s_add_u32 s30, s72, s30
	s_addc_u32 s31, s73, s31
	s_and_b64 s[40:41], s[4:5], exec
	s_cselect_b32 s25, s31, s39
	s_cselect_b32 s58, s30, s38
	s_add_u32 s36, s36, 0x40080
	s_addc_u32 s37, s37, 0
	s_add_u32 s59, s38, 0x100
	s_addc_u32 s60, s39, 0
	s_mov_b32 s61, -2
.LBB0_877:
	s_cmp_eq_u32 s100, 0
	s_cbranch_scc1 .Ldhs8_idle
	s_cmp_lt_i32 s61, 6
	s_cbranch_scc0 .Ldhs8_hi
	s_cmp_lt_i32 s61, 2
	s_cbranch_scc0 .Ldhs8_q1
	s_cmp_lt_i32 s61, 0
	s_cbranch_scc0 .Ldhs8_g9
	global_store_dwordx4 v255, v[226:229], s[16:17] sc1 nt
	s_branch .Ldhs8_done

.Ldhs8_done:
	ds_read_b128 v[150:153], v147
	ds_read_b128 v[154:157], v147 offset:1024
	ds_read_b128 v[158:161], v147 offset:2048
	ds_read_b128 v[162:165], v147 offset:3072
	ds_read_b128 v[166:169], v148
	ds_read_b128 v[170:173], v148 offset:1024
	ds_read_b128 v[174:177], v148 offset:2048
	ds_read_b128 v[178:181], v148 offset:3072
	s_add_u32 s38, s36, 0xfffc0080
	s_addc_u32 s39, s37, -1
	s_cmp_eq_u32 s61, 12
	s_cselect_b32 s41, s27, s39
	s_cselect_b32 s40, s57, s38
	s_cselect_b32 s39, s25, s60
	s_cselect_b32 s38, s58, s59
	v_lshl_add_u64 v[214:215], s[36:37], 0, v[136:137]
	s_add_i32 m0, s35, 0xc000
	ds_read_b128 v[182:185], v149
	ds_read_b128 v[186:189], v149 offset:1024
	ds_read_b128 v[190:193], v149 offset:2048
	ds_read_b128 v[194:197], v149 offset:3072
	ds_read_b128 v[198:201], v149 offset:4096
	ds_read_b128 v[202:205], v149 offset:5120
	ds_read_b128 v[206:209], v149 offset:6144
	ds_read_b128 v[210:213], v149 offset:7168
	global_load_lds_dwordx4 v[214:215], off
	v_lshl_add_u64 v[214:215], s[36:37], 0, v[138:139]
	s_add_i32 m0, s35, 0xe000
	s_nop 0
	global_load_lds_dwordx4 v[214:215], off
	s_cmp_eq_u32 s61, -2
	s_cbranch_scc1 .Lzs_hi
.Lzs_hi_back:
	s_waitcnt vmcnt(9)
	s_waitcnt lgkmcnt(0)
	s_barrier
	s_setprio 1
	s_waitcnt lgkmcnt(0)
	v_mfma_f32_16x16x32_bf16 v[124:127], v[150:153], v[182:185], v[124:127]
	v_mfma_f32_16x16x32_bf16 v[120:123], v[158:161], v[182:185], v[120:123]
	v_mfma_f32_16x16x32_bf16 v[108:111], v[150:153], v[190:193], v[108:111]
	v_mfma_f32_16x16x32_bf16 v[104:107], v[158:161], v[190:193], v[104:107]
	v_mfma_f32_16x16x32_bf16 v[92:95], v[150:153], v[198:201], v[92:95]
	v_mfma_f32_16x16x32_bf16 v[88:91], v[158:161], v[198:201], v[88:91]
	v_mfma_f32_16x16x32_bf16 v[76:79], v[150:153], v[206:209], v[76:79]
	v_mfma_f32_16x16x32_bf16 v[72:75], v[158:161], v[206:209], v[72:75]
	v_mfma_f32_16x16x32_bf16 v[124:127], v[154:157], v[186:189], v[124:127]
	v_mfma_f32_16x16x32_bf16 v[120:123], v[162:165], v[186:189], v[120:123]
	v_mfma_f32_16x16x32_bf16 v[108:111], v[154:157], v[194:197], v[108:111]
	v_mfma_f32_16x16x32_bf16 v[104:107], v[162:165], v[194:197], v[104:107]
	v_mfma_f32_16x16x32_bf16 v[92:95], v[154:157], v[202:205], v[92:95]
	v_mfma_f32_16x16x32_bf16 v[88:91], v[162:165], v[202:205], v[88:91]
	v_mfma_f32_16x16x32_bf16 v[76:79], v[154:157], v[210:213], v[76:79]
	v_mfma_f32_16x16x32_bf16 v[72:75], v[162:165], v[210:213], v[72:75]
	s_setprio 0
	s_setprio 1
	v_mfma_f32_16x16x32_bf16 v[116:119], v[166:169], v[182:185], v[116:119]
	v_mfma_f32_16x16x32_bf16 v[112:115], v[174:177], v[182:185], v[112:115]
	v_mfma_f32_16x16x32_bf16 v[100:103], v[166:169], v[190:193], v[100:103]
	v_mfma_f32_16x16x32_bf16 v[96:99], v[174:177], v[190:193], v[96:99]
	v_mfma_f32_16x16x32_bf16 v[84:87], v[166:169], v[198:201], v[84:87]
	v_mfma_f32_16x16x32_bf16 v[80:83], v[174:177], v[198:201], v[80:83]
	v_mfma_f32_16x16x32_bf16 v[68:71], v[166:169], v[206:209], v[68:71]
	v_mfma_f32_16x16x32_bf16 v[64:67], v[174:177], v[206:209], v[64:67]
	v_mfma_f32_16x16x32_bf16 v[116:119], v[170:173], v[186:189], v[116:119]
	v_mfma_f32_16x16x32_bf16 v[112:115], v[178:181], v[186:189], v[112:115]
	v_mfma_f32_16x16x32_bf16 v[100:103], v[170:173], v[194:197], v[100:103]
	v_mfma_f32_16x16x32_bf16 v[96:99], v[178:181], v[194:197], v[96:99]
	v_mfma_f32_16x16x32_bf16 v[84:87], v[170:173], v[202:205], v[84:87]
	v_mfma_f32_16x16x32_bf16 v[80:83], v[178:181], v[202:205], v[80:83]
	v_mfma_f32_16x16x32_bf16 v[68:71], v[170:173], v[210:213], v[68:71]
	v_mfma_f32_16x16x32_bf16 v[64:67], v[178:181], v[210:213], v[64:67]
	s_setprio 0
	s_barrier
	s_add_i32 s62, s50, s3
	v_lshl_add_u64 v[214:215], s[38:39], 0, v[130:131]
	s_mov_b32 m0, s62
	ds_read_b128 v[182:185], v149 offset:16384
	ds_read_b128 v[186:189], v149 offset:17408
	ds_read_b128 v[190:193], v149 offset:18432
	ds_read_b128 v[194:197], v149 offset:19456
	ds_read_b128 v[198:201], v149 offset:20480
	ds_read_b128 v[202:205], v149 offset:21504
	ds_read_b128 v[206:209], v149 offset:22528
	ds_read_b128 v[210:213], v149 offset:23552
	global_load_lds_dwordx4 v[214:215], off
	s_add_i32 m0, s62, 0x2000
	s_add_u32 s62, s38, 0x40000
	v_lshl_add_u64 v[216:217], s[38:39], 0, v[134:135]
	s_addc_u32 s63, s39, 0
	s_add_i32 s64, s51, s3
	global_load_lds_dwordx4 v[216:217], off
	v_lshl_add_u64 v[218:219], s[62:63], 0, v[130:131]
	s_mov_b32 m0, s64
	v_lshl_add_u64 v[222:223], s[40:41], 0, v[132:133]
	global_load_lds_dwordx4 v[218:219], off
	v_lshl_add_u64 v[218:219], s[62:63], 0, v[134:135]
	s_add_i32 m0, s64, 0x2000
	s_nop 0
	global_load_lds_dwordx4 v[218:219], off
	v_lshl_add_u64 v[218:219], s[40:41], 0, v[128:129]
	s_mov_b32 m0, s35
	s_nop 0
	global_load_lds_dwordx4 v[218:219], off
	s_mov_b32 m0, s42
	s_nop 0
	global_load_lds_dwordx4 v[222:223], off
	s_cmp_eq_u32 s61, -2
	s_cbranch_scc1 .Lzs_lo
.Lzs_lo_back:
	s_waitcnt vmcnt(9)
	s_waitcnt lgkmcnt(0)
	s_barrier
	s_setprio 1
	s_waitcnt lgkmcnt(0)
	v_mfma_f32_16x16x32_bf16 v[60:63], v[150:153], v[182:185], v[60:63]
	v_mfma_f32_16x16x32_bf16 v[56:59], v[158:161], v[182:185], v[56:59]
	v_mfma_f32_16x16x32_bf16 v[44:47], v[150:153], v[190:193], v[44:47]
	v_mfma_f32_16x16x32_bf16 v[40:43], v[158:161], v[190:193], v[40:43]
	v_mfma_f32_16x16x32_bf16 v[28:31], v[150:153], v[198:201], v[28:31]
	v_mfma_f32_16x16x32_bf16 v[24:27], v[158:161], v[198:201], v[24:27]
	v_mfma_f32_16x16x32_bf16 v[12:15], v[150:153], v[206:209], v[12:15]
	v_mfma_f32_16x16x32_bf16 v[8:11], v[158:161], v[206:209], v[8:11]
	v_mfma_f32_16x16x32_bf16 v[60:63], v[154:157], v[186:189], v[60:63]
	v_mfma_f32_16x16x32_bf16 v[56:59], v[162:165], v[186:189], v[56:59]
	v_mfma_f32_16x16x32_bf16 v[44:47], v[154:157], v[194:197], v[44:47]
	v_mfma_f32_16x16x32_bf16 v[40:43], v[162:165], v[194:197], v[40:43]
	v_mfma_f32_16x16x32_bf16 v[28:31], v[154:157], v[202:205], v[28:31]
	v_mfma_f32_16x16x32_bf16 v[24:27], v[162:165], v[202:205], v[24:27]
	v_mfma_f32_16x16x32_bf16 v[12:15], v[154:157], v[210:213], v[12:15]
	v_mfma_f32_16x16x32_bf16 v[8:11], v[162:165], v[210:213], v[8:11]
	s_setprio 0
	s_setprio 1
	v_mfma_f32_16x16x32_bf16 v[52:55], v[166:169], v[182:185], v[52:55]
	v_mfma_f32_16x16x32_bf16 v[48:51], v[174:177], v[182:185], v[48:51]
	v_mfma_f32_16x16x32_bf16 v[36:39], v[166:169], v[190:193], v[36:39]
	v_mfma_f32_16x16x32_bf16 v[32:35], v[174:177], v[190:193], v[32:35]
	v_mfma_f32_16x16x32_bf16 v[20:23], v[166:169], v[198:201], v[20:23]
	v_mfma_f32_16x16x32_bf16 v[16:19], v[174:177], v[198:201], v[16:19]
	v_mfma_f32_16x16x32_bf16 v[4:7], v[166:169], v[206:209], v[4:7]
	v_mfma_f32_16x16x32_bf16 v[0:3], v[174:177], v[206:209], v[0:3]
	v_mfma_f32_16x16x32_bf16 v[52:55], v[170:173], v[186:189], v[52:55]
	v_mfma_f32_16x16x32_bf16 v[48:51], v[178:181], v[186:189], v[48:51]
	v_mfma_f32_16x16x32_bf16 v[36:39], v[170:173], v[194:197], v[36:39]
	v_mfma_f32_16x16x32_bf16 v[32:35], v[178:181], v[194:197], v[32:35]
	v_mfma_f32_16x16x32_bf16 v[20:23], v[170:173], v[202:205], v[20:23]
	v_mfma_f32_16x16x32_bf16 v[16:19], v[178:181], v[202:205], v[16:19]
	v_mfma_f32_16x16x32_bf16 v[4:7], v[170:173], v[210:213], v[4:7]
	v_mfma_f32_16x16x32_bf16 v[0:3], v[178:181], v[210:213], v[0:3]
	s_setprio 0
	s_barrier
	s_add_i32 s62, 0, 0x18000
	s_add_i32 s63, 0, 0x1c000
	v_add_u32_e32 v162, s62, v145
	v_add_u32_e32 v178, s63, v145
	ds_read_b128 v[150:153], v162
	ds_read_b128 v[154:157], v162 offset:1024
	ds_read_b128 v[158:161], v162 offset:2048
	ds_read_b128 v[162:165], v162 offset:3072
	ds_read_b128 v[166:169], v178
	ds_read_b128 v[170:173], v178 offset:1024
	ds_read_b128 v[174:177], v178 offset:2048
	ds_read_b128 v[178:181], v178 offset:3072
	s_add_u32 s40, s40, 0x40000
	s_addc_u32 s41, s41, 0
	s_mov_b32 m0, s43
	v_lshl_add_u64 v[224:225], s[40:41], 0, v[128:129]
	ds_read_b128 v[182:185], v149 offset:32768
	ds_read_b128 v[186:189], v149 offset:33792
	ds_read_b128 v[190:193], v149 offset:34816
	ds_read_b128 v[194:197], v149 offset:35840
	ds_read_b128 v[198:201], v149 offset:36864
	ds_read_b128 v[202:205], v149 offset:37888
	ds_read_b128 v[206:209], v149 offset:38912
	ds_read_b128 v[210:213], v149 offset:39936
	global_load_lds_dwordx4 v[224:225], off
	v_lshl_add_u64 v[224:225], s[40:41], 0, v[132:133]
	s_mov_b32 m0, s44
	s_nop 0
	global_load_lds_dwordx4 v[224:225], off
	s_waitcnt vmcnt(8)
	s_waitcnt lgkmcnt(0)
	s_barrier
	s_setprio 1
	s_waitcnt lgkmcnt(0)
	v_mfma_f32_16x16x32_bf16 v[124:127], v[150:153], v[182:185], v[124:127]
	v_mfma_f32_16x16x32_bf16 v[120:123], v[158:161], v[182:185], v[120:123]
	v_mfma_f32_16x16x32_bf16 v[108:111], v[150:153], v[190:193], v[108:111]
	v_mfma_f32_16x16x32_bf16 v[104:107], v[158:161], v[190:193], v[104:107]
	v_mfma_f32_16x16x32_bf16 v[92:95], v[150:153], v[198:201], v[92:95]
	v_mfma_f32_16x16x32_bf16 v[88:91], v[158:161], v[198:201], v[88:91]
	v_mfma_f32_16x16x32_bf16 v[76:79], v[150:153], v[206:209], v[76:79]
	v_mfma_f32_16x16x32_bf16 v[72:75], v[158:161], v[206:209], v[72:75]
	v_mfma_f32_16x16x32_bf16 v[124:127], v[154:157], v[186:189], v[124:127]
	v_mfma_f32_16x16x32_bf16 v[120:123], v[162:165], v[186:189], v[120:123]
	v_mfma_f32_16x16x32_bf16 v[108:111], v[154:157], v[194:197], v[108:111]
	v_mfma_f32_16x16x32_bf16 v[104:107], v[162:165], v[194:197], v[104:107]
	v_mfma_f32_16x16x32_bf16 v[92:95], v[154:157], v[202:205], v[92:95]
	v_mfma_f32_16x16x32_bf16 v[88:91], v[162:165], v[202:205], v[88:91]
	v_mfma_f32_16x16x32_bf16 v[76:79], v[154:157], v[210:213], v[76:79]
	v_mfma_f32_16x16x32_bf16 v[72:75], v[162:165], v[210:213], v[72:75]
	s_setprio 0
	s_setprio 1
	v_mfma_f32_16x16x32_bf16 v[116:119], v[166:169], v[182:185], v[116:119]
	v_mfma_f32_16x16x32_bf16 v[112:115], v[174:177], v[182:185], v[112:115]
	v_mfma_f32_16x16x32_bf16 v[100:103], v[166:169], v[190:193], v[100:103]
	v_mfma_f32_16x16x32_bf16 v[96:99], v[174:177], v[190:193], v[96:99]
	v_mfma_f32_16x16x32_bf16 v[84:87], v[166:169], v[198:201], v[84:87]
	v_mfma_f32_16x16x32_bf16 v[80:83], v[174:177], v[198:201], v[80:83]
	v_mfma_f32_16x16x32_bf16 v[68:71], v[166:169], v[206:209], v[68:71]
	v_mfma_f32_16x16x32_bf16 v[64:67], v[174:177], v[206:209], v[64:67]
	v_mfma_f32_16x16x32_bf16 v[116:119], v[170:173], v[186:189], v[116:119]
	v_mfma_f32_16x16x32_bf16 v[112:115], v[178:181], v[186:189], v[112:115]
	v_mfma_f32_16x16x32_bf16 v[100:103], v[170:173], v[194:197], v[100:103]
	v_mfma_f32_16x16x32_bf16 v[96:99], v[178:181], v[194:197], v[96:99]
	v_mfma_f32_16x16x32_bf16 v[84:87], v[170:173], v[202:205], v[84:87]
	v_mfma_f32_16x16x32_bf16 v[80:83], v[178:181], v[202:205], v[80:83]
	v_mfma_f32_16x16x32_bf16 v[68:71], v[170:173], v[210:213], v[68:71]
	v_mfma_f32_16x16x32_bf16 v[64:67], v[178:181], v[210:213], v[64:67]
	s_setprio 0
	s_barrier
	s_add_i32 s40, s62, s3
	v_lshl_add_u64 v[214:215], v[214:215], 0, s[12:13]
	s_mov_b32 m0, s40
	ds_read_b128 v[182:185], v149 offset:49152
	ds_read_b128 v[186:189], v149 offset:50176
	ds_read_b128 v[190:193], v149 offset:51200
	ds_read_b128 v[194:197], v149 offset:52224
	ds_read_b128 v[198:201], v149 offset:53248
	ds_read_b128 v[202:205], v149 offset:54272
	ds_read_b128 v[206:209], v149 offset:55296
	ds_read_b128 v[210:213], v149 offset:56320
	global_load_lds_dwordx4 v[214:215], off
	s_add_i32 m0, s40, 0x2000
	s_add_u32 s38, s38, 0x40080
	v_lshl_add_u64 v[214:215], v[216:217], 0, s[12:13]
	s_addc_u32 s39, s39, 0
	s_add_i32 s40, s63, s3
	global_load_lds_dwordx4 v[214:215], off
	v_lshl_add_u64 v[214:215], s[38:39], 0, v[130:131]
	s_mov_b32 m0, s40
	s_nop 0
	global_load_lds_dwordx4 v[214:215], off
	v_lshl_add_u64 v[214:215], s[38:39], 0, v[134:135]
	s_add_i32 m0, s40, 0x2000
	s_nop 0
	global_load_lds_dwordx4 v[214:215], off
	v_lshl_add_u64 v[214:215], v[218:219], 0, s[12:13]
	s_mov_b32 m0, s47
	s_nop 0
	global_load_lds_dwordx4 v[214:215], off
	v_lshl_add_u64 v[214:215], v[222:223], 0, s[12:13]
	s_mov_b32 m0, s48
	s_nop 0
	global_load_lds_dwordx4 v[214:215], off
	s_waitcnt vmcnt(8)
	s_waitcnt lgkmcnt(0)
	s_barrier
	s_setprio 1
	s_waitcnt lgkmcnt(0)
	v_mfma_f32_16x16x32_bf16 v[60:63], v[150:153], v[182:185], v[60:63]
	v_mfma_f32_16x16x32_bf16 v[56:59], v[158:161], v[182:185], v[56:59]
	v_mfma_f32_16x16x32_bf16 v[44:47], v[150:153], v[190:193], v[44:47]
	v_mfma_f32_16x16x32_bf16 v[40:43], v[158:161], v[190:193], v[40:43]
	v_mfma_f32_16x16x32_bf16 v[28:31], v[150:153], v[198:201], v[28:31]
	v_mfma_f32_16x16x32_bf16 v[24:27], v[158:161], v[198:201], v[24:27]
	v_mfma_f32_16x16x32_bf16 v[12:15], v[150:153], v[206:209], v[12:15]
	v_mfma_f32_16x16x32_bf16 v[8:11], v[158:161], v[206:209], v[8:11]
	v_mfma_f32_16x16x32_bf16 v[60:63], v[154:157], v[186:189], v[60:63]
	v_mfma_f32_16x16x32_bf16 v[56:59], v[162:165], v[186:189], v[56:59]
	v_mfma_f32_16x16x32_bf16 v[44:47], v[154:157], v[194:197], v[44:47]
	v_mfma_f32_16x16x32_bf16 v[40:43], v[162:165], v[194:197], v[40:43]
	v_mfma_f32_16x16x32_bf16 v[28:31], v[154:157], v[202:205], v[28:31]
	v_mfma_f32_16x16x32_bf16 v[24:27], v[162:165], v[202:205], v[24:27]
	v_mfma_f32_16x16x32_bf16 v[12:15], v[154:157], v[210:213], v[12:15]
	v_mfma_f32_16x16x32_bf16 v[8:11], v[162:165], v[210:213], v[8:11]
	s_setprio 0
	s_setprio 1
	v_mfma_f32_16x16x32_bf16 v[52:55], v[166:169], v[182:185], v[52:55]
	v_mfma_f32_16x16x32_bf16 v[48:51], v[174:177], v[182:185], v[48:51]
	v_mfma_f32_16x16x32_bf16 v[36:39], v[166:169], v[190:193], v[36:39]
	v_mfma_f32_16x16x32_bf16 v[32:35], v[174:177], v[190:193], v[32:35]
	v_mfma_f32_16x16x32_bf16 v[20:23], v[166:169], v[198:201], v[20:23]
	v_mfma_f32_16x16x32_bf16 v[16:19], v[174:177], v[198:201], v[16:19]
	v_mfma_f32_16x16x32_bf16 v[4:7], v[166:169], v[206:209], v[4:7]
	v_mfma_f32_16x16x32_bf16 v[0:3], v[174:177], v[206:209], v[0:3]
	v_mfma_f32_16x16x32_bf16 v[52:55], v[170:173], v[186:189], v[52:55]
	v_mfma_f32_16x16x32_bf16 v[48:51], v[178:181], v[186:189], v[48:51]
	v_mfma_f32_16x16x32_bf16 v[36:39], v[170:173], v[194:197], v[36:39]
	v_mfma_f32_16x16x32_bf16 v[32:35], v[178:181], v[194:197], v[32:35]
	v_mfma_f32_16x16x32_bf16 v[20:23], v[170:173], v[202:205], v[20:23]
	v_mfma_f32_16x16x32_bf16 v[16:19], v[178:181], v[202:205], v[16:19]
	v_mfma_f32_16x16x32_bf16 v[4:7], v[170:173], v[210:213], v[4:7]
	v_mfma_f32_16x16x32_bf16 v[0:3], v[178:181], v[210:213], v[0:3]
	s_setprio 0
	s_barrier
	s_add_i32 s61, s61, 2
	s_add_u32 s36, s36, 0x100
	s_addc_u32 s37, s37, 0
	s_add_u32 s59, s59, 0x100
	s_addc_u32 s60, s60, 0
	s_cmp_gt_u32 s61, 13
	s_cbranch_scc0 .LBB0_877
	s_and_b64 vcc, exec, s[14:15]
	s_cbranch_vccz .LBB0_880
	s_barrier

.Lzs_hi:
	v_mov_b64_e32 v[64:65], 0
	v_mov_b64_e32 v[66:67], 0
	v_mov_b64_e32 v[68:69], 0
	v_mov_b64_e32 v[70:71], 0
	v_mov_b64_e32 v[72:73], 0
	v_mov_b64_e32 v[74:75], 0
	v_mov_b64_e32 v[76:77], 0
	v_mov_b64_e32 v[78:79], 0
	v_mov_b64_e32 v[80:81], 0
	v_mov_b64_e32 v[82:83], 0
	v_mov_b64_e32 v[84:85], 0
	v_mov_b64_e32 v[86:87], 0
	v_mov_b64_e32 v[88:89], 0
	v_mov_b64_e32 v[90:91], 0
	v_mov_b64_e32 v[92:93], 0
	v_mov_b64_e32 v[94:95], 0
	v_mov_b64_e32 v[96:97], 0
	v_mov_b64_e32 v[98:99], 0
	v_mov_b64_e32 v[100:101], 0
	v_mov_b64_e32 v[102:103], 0
	v_mov_b64_e32 v[104:105], 0
	v_mov_b64_e32 v[106:107], 0
	v_mov_b64_e32 v[108:109], 0
	v_mov_b64_e32 v[110:111], 0
	v_mov_b64_e32 v[112:113], 0
	v_mov_b64_e32 v[114:115], 0
	v_mov_b64_e32 v[116:117], 0
	v_mov_b64_e32 v[118:119], 0
	v_mov_b64_e32 v[120:121], 0
	v_mov_b64_e32 v[122:123], 0
	v_mov_b64_e32 v[124:125], 0
	v_mov_b64_e32 v[126:127], 0
	s_branch .Lzs_hi_back
.Lzs_lo:
	v_mov_b64_e32 v[0:1], 0
	v_mov_b64_e32 v[2:3], 0
	v_mov_b64_e32 v[4:5], 0
	v_mov_b64_e32 v[6:7], 0
	v_mov_b64_e32 v[8:9], 0
	v_mov_b64_e32 v[10:11], 0
	v_mov_b64_e32 v[12:13], 0
	v_mov_b64_e32 v[14:15], 0
	v_mov_b64_e32 v[16:17], 0
	v_mov_b64_e32 v[18:19], 0
	v_mov_b64_e32 v[20:21], 0
	v_mov_b64_e32 v[22:23], 0
	v_mov_b64_e32 v[24:25], 0
	v_mov_b64_e32 v[26:27], 0
	v_mov_b64_e32 v[28:29], 0
	v_mov_b64_e32 v[30:31], 0
	v_mov_b64_e32 v[32:33], 0
	v_mov_b64_e32 v[34:35], 0
	v_mov_b64_e32 v[36:37], 0
	v_mov_b64_e32 v[38:39], 0
	v_mov_b64_e32 v[40:41], 0
	v_mov_b64_e32 v[42:43], 0
	v_mov_b64_e32 v[44:45], 0
	v_mov_b64_e32 v[46:47], 0
	v_mov_b64_e32 v[48:49], 0
	v_mov_b64_e32 v[50:51], 0
	v_mov_b64_e32 v[52:53], 0
	v_mov_b64_e32 v[54:55], 0
	v_mov_b64_e32 v[56:57], 0
	v_mov_b64_e32 v[58:59], 0
	v_mov_b64_e32 v[60:61], 0
	v_mov_b64_e32 v[62:63], 0
	s_branch .Lzs_lo_back
